# v047 + packed f32 ops in the GLA chunk units split into scalar pairs + redundant wait/barrier pair removed at the start of the cross-attention unit
# baseline (speedup 1.0000x reference)
; __device__ __forceinline__ float bflo(unsigned w) { return __uint_as_float(w << 16); }
; __device__ __forceinline__ float bfhi(unsigned w) { return __uint_as_float(w & 0xffff0000u); }
; __device__ __forceinline__ float shx(float v, int off, int lane) { return __int_as_float(__builtin_amdgcn_ds_bpermute((lane ^ off) << 2, __float_as_int(v))); }
; __global__ void __launch_bounds__(512, 2) hybrid_fwd(Params p) {
;     ...
;                     const int v = u - 516, hd = v >> 4, sl = v & 15; float mxn = 0.f;
; #pragma unroll 4
;                     for (int ps = 0; ps < 16; ++ps) {
;                         const int key = sl * 512 + ps * 32 + (tid >> 4);
;                         const u32x4 kk = *(const u32x4*)(PROJ + (size_t)key * NP + PJ_FK + hd * 128 + (tid & 15) * 8);
;                         float q2 = bflo(kk.x) * bflo(kk.x) + bfhi(kk.x) * bfhi(kk.x) + bflo(kk.y) * bflo(kk.y) + bfhi(kk.y) * bfhi(kk.y) + bflo(kk.z) * bflo(kk.z) + bfhi(kk.z) * bfhi(kk.z) + bflo(kk.w) * bflo(kk.w) + bfhi(kk.w) * bfhi(kk.w);
;                         q2 += shx(q2, 1, lane); q2 += shx(q2, 2, lane); q2 += shx(q2, 4, lane); q2 += shx(q2, 8, lane);
;                         mxn = fmaxf(mxn, q2);
;                     }
;                     mxn = fmaxf(mxn, shx(mxn, 16, lane)); mxn = fmaxf(mxn, shx(mxn, 32, lane));
;                     if (lane == 0) atomicMax(KNB + l * 4 + hd, __float_as_uint(mxn));
.LBB0_449:
	v_lshl_add_u64 v[10:11], v[6:7], 0, s[18:19]
	flat_load_dwordx4 v[10:13], v[10:11]
	s_waitcnt vmcnt(0) lgkmcnt(0)
	v_lshlrev_b32_e32 v14, 16, v10
	v_and_b32_e32 v15, 0xffff0000, v10
	v_mul_f32_e32 v14, v14, v14
	v_mul_f32_e32 v15, v15, v15
	v_and_b32_e32 v10, 0xffff0000, v11
	v_lshlrev_b32_e32 v11, 16, v11
	v_mul_f32_e32 v10, v10, v10
	v_mul_f32_e32 v11, v11, v11
	v_add_f32_e32 v9, v14, v15
	v_and_b32_e32 v70, 0xffff0000, v12
	v_lshlrev_b32_e32 v71, 16, v12
	v_add_f32_e32 v9, v11, v9
	v_mul_f32_e32 v70, v70, v70
	v_mul_f32_e32 v71, v71, v71
	v_add_f32_e32 v9, v10, v9
	v_and_b32_e32 v12, 0xffff0000, v13
	v_lshlrev_b32_e32 v13, 16, v13
	v_add_f32_e32 v9, v71, v9
	v_mul_f32_e32 v12, v12, v12
	v_mul_f32_e32 v13, v13, v13
	v_add_f32_e32 v9, v70, v9
	v_add_f32_e32 v9, v13, v9
	v_add_f32_e32 v9, v12, v9
	ds_bpermute_b32 v10, v54, v9
	s_waitcnt lgkmcnt(0)
	v_add_f32_e32 v9, v9, v10
	ds_bpermute_b32 v10, v55, v9
	s_waitcnt lgkmcnt(0)
	v_add_f32_e32 v9, v9, v10
	ds_bpermute_b32 v10, v56, v9
	s_waitcnt lgkmcnt(0)
	v_add_f32_e32 v9, v9, v10
	ds_bpermute_b32 v10, v57, v9
	s_waitcnt lgkmcnt(0)
	v_add_f32_e32 v9, v9, v10
	v_lshl_add_u64 v[10:11], v[4:5], 0, s[18:19]
	flat_load_dwordx4 v[10:13], v[10:11]
	s_waitcnt vmcnt(0) lgkmcnt(0)
	v_lshlrev_b32_e32 v14, 16, v10
	v_and_b32_e32 v15, 0xffff0000, v10
	v_mul_f32_e32 v14, v14, v14
	v_mul_f32_e32 v15, v15, v15
	v_and_b32_e32 v10, 0xffff0000, v11
	v_lshlrev_b32_e32 v11, 16, v11
	v_mul_f32_e32 v10, v10, v10
	v_mul_f32_e32 v11, v11, v11
	v_add_f32_e32 v14, v14, v15
	v_and_b32_e32 v70, 0xffff0000, v12
	v_lshlrev_b32_e32 v71, 16, v12
	v_add_f32_e32 v11, v11, v14
	v_mul_f32_e32 v70, v70, v70
	v_mul_f32_e32 v71, v71, v71
	v_add_f32_e32 v10, v10, v11
	v_and_b32_e32 v12, 0xffff0000, v13
	v_lshlrev_b32_e32 v13, 16, v13
	v_add_f32_e32 v10, v71, v10
	v_mul_f32_e32 v12, v12, v12
	v_mul_f32_e32 v13, v13, v13
	v_add_f32_e32 v10, v70, v10
	v_add_f32_e32 v10, v13, v10
	v_add_f32_e32 v10, v12, v10
	ds_bpermute_b32 v11, v54, v10
	s_waitcnt lgkmcnt(0)
	v_add_f32_e32 v10, v10, v11
	ds_bpermute_b32 v11, v55, v10
	s_waitcnt lgkmcnt(0)
	v_add_f32_e32 v10, v10, v11
	ds_bpermute_b32 v11, v56, v10
	s_waitcnt lgkmcnt(0)
	v_add_f32_e32 v10, v10, v11
	ds_bpermute_b32 v11, v57, v10
	s_waitcnt lgkmcnt(0)
	v_add_f32_e32 v10, v10, v11
	v_max3_f32 v69, v8, v9, v10
	v_lshl_add_u64 v[8:9], v[2:3], 0, s[18:19]
	flat_load_dwordx4 v[8:11], v[8:9]
	s_waitcnt vmcnt(0) lgkmcnt(0)
	v_lshlrev_b32_e32 v12, 16, v8
	v_and_b32_e32 v13, 0xffff0000, v8
	v_mul_f32_e32 v12, v12, v12
	v_mul_f32_e32 v13, v13, v13
	v_and_b32_e32 v8, 0xffff0000, v9
	v_lshlrev_b32_e32 v9, 16, v9
	v_mul_f32_e32 v8, v8, v8
	v_mul_f32_e32 v9, v9, v9
	v_add_f32_e32 v12, v12, v13
	v_and_b32_e32 v14, 0xffff0000, v10
	v_lshlrev_b32_e32 v15, 16, v10
	v_add_f32_e32 v9, v9, v12
	v_mul_f32_e32 v14, v14, v14
	v_mul_f32_e32 v15, v15, v15
	v_add_f32_e32 v8, v8, v9
	v_and_b32_e32 v10, 0xffff0000, v11
	v_lshlrev_b32_e32 v11, 16, v11
	v_add_f32_e32 v8, v15, v8
	v_mul_f32_e32 v10, v10, v10
	v_mul_f32_e32 v11, v11, v11
	v_add_f32_e32 v8, v14, v8
	v_add_f32_e32 v8, v11, v8
	v_add_f32_e32 v8, v10, v8
	ds_bpermute_b32 v9, v54, v8
	s_waitcnt lgkmcnt(0)
	v_add_f32_e32 v8, v8, v9
	ds_bpermute_b32 v9, v55, v8
	s_waitcnt lgkmcnt(0)
	v_add_f32_e32 v8, v8, v9
	ds_bpermute_b32 v9, v56, v8
	s_waitcnt lgkmcnt(0)
	v_add_f32_e32 v8, v8, v9
	ds_bpermute_b32 v9, v57, v8
	s_waitcnt lgkmcnt(0)
	v_add_f32_e32 v70, v8, v9
	v_lshl_add_u64 v[8:9], v[0:1], 0, s[18:19]
	flat_load_dwordx4 v[8:11], v[8:9]
	s_add_u32 s18, s18, 0xe0000
	s_addc_u32 s19, s19, 0
	s_cmp_eq_u32 s18, 0x380000
	s_waitcnt vmcnt(0) lgkmcnt(0)
	v_lshlrev_b32_e32 v12, 16, v8
	v_and_b32_e32 v13, 0xffff0000, v8
	v_mul_f32_e32 v12, v12, v12
	v_mul_f32_e32 v13, v13, v13
	v_and_b32_e32 v8, 0xffff0000, v9
	v_lshlrev_b32_e32 v9, 16, v9
	v_mul_f32_e32 v8, v8, v8
	v_mul_f32_e32 v9, v9, v9
	v_add_f32_e32 v12, v12, v13
	v_and_b32_e32 v14, 0xffff0000, v10
	v_lshlrev_b32_e32 v15, 16, v10
	v_add_f32_e32 v9, v9, v12
	v_mul_f32_e32 v14, v14, v14
	v_mul_f32_e32 v15, v15, v15
	v_add_f32_e32 v8, v8, v9
	v_and_b32_e32 v10, 0xffff0000, v11
	v_lshlrev_b32_e32 v11, 16, v11
	v_add_f32_e32 v8, v15, v8
	v_mul_f32_e32 v10, v10, v10
	v_mul_f32_e32 v11, v11, v11
	v_add_f32_e32 v8, v14, v8
	v_add_f32_e32 v8, v11, v8
	v_add_f32_e32 v8, v10, v8
	ds_bpermute_b32 v9, v54, v8
	s_waitcnt lgkmcnt(0)
	v_add_f32_e32 v8, v8, v9
	ds_bpermute_b32 v9, v55, v8
	s_waitcnt lgkmcnt(0)
	v_add_f32_e32 v8, v8, v9
	ds_bpermute_b32 v9, v56, v8
	s_waitcnt lgkmcnt(0)
	v_add_f32_e32 v8, v8, v9
	ds_bpermute_b32 v9, v57, v8
	s_waitcnt lgkmcnt(0)
	v_add_f32_e32 v8, v8, v9
	v_max3_f32 v8, v69, v70, v8
	s_cbranch_scc0 .LBB0_449
	ds_bpermute_b32 v0, v58, v8
	v_max_f32_e32 v1, v8, v8
	s_waitcnt lgkmcnt(0)
	v_max_f32_e32 v0, v0, v0
	v_max_f32_e32 v0, v1, v0
	ds_bpermute_b32 v1, v59, v0
	s_and_saveexec_b64 s[18:19], s[0:1]
	s_cbranch_execz .LBB0_452
	s_add_i32 s3, s2, 0xfffffdfc
	s_lshr_b32 s3, s3, 2
	s_and_b32 s3, s3, 0x3ffffffc
	v_readlane_b32 s35, v255, 45
	s_add_u32 s44, s35, s3
	v_readlane_b32 s3, v255, 44
	s_waitcnt lgkmcnt(0)
	v_max_f32_e32 v1, v1, v1
	v_max_f32_e32 v0, v0, v0
	s_addc_u32 s45, s3, 0
	v_max_f32_e32 v2, v0, v1
	v_mov_b64_e32 v[0:1], s[44:45]
	flat_atomic_umax v[0:1], v2

; template <int MODEC>
; __device__ __forceinline__ void gla_unit(LAS unsigned char* lds, const int tid_in, const Params& p, int l, int hh, int n) {
;     ...
;         if (h2 == 0) ss[tt * 4 + dvb] = part;
;         __syncthreads();
.LBB0_606:
	s_or_b64 exec, exec, s[0:1]
	v_add_u32_e32 v16, 0, v17
	s_waitcnt lgkmcnt(0)
	s_barrier
; __device__ __forceinline__ unsigned cvt_pk_bf16(float lo, float hi) { unsigned r; asm("v_cvt_pk_bf16_f32 %0, %1, %2" : "=v"(r) : "v"(lo), "v"(hi)); return r; }
; __device__ __forceinline__ float bflo(unsigned w) { return __uint_as_float(w << 16); }
; __device__ __forceinline__ float bfhi(unsigned w) { return __uint_as_float(w & 0xffff0000u); }
; template <int MODEC>
; __device__ __forceinline__ void gla_unit(LAS unsigned char* lds, const int tid_in, const Params& p, int l, int hh, int n) {
;     ...
;         const float tot = (ss[tt * 4] + ss[tt * 4 + 1]) + (ss[tt * 4 + 2] + ss[tt * 4 + 3]);
;         const float rstd = rsqrtf(tot * (1.f / 128.f) + EPS);
;         bf16_t* op = (bf16_t*)(ws + WS_O) + (size_t)(t0 + tt) * D_ + 1536 + hh * 128;
;         const bf16_t* grp = proj + (size_t)(t0 + tt) * NP + PJ_GR + hh * 128;
;         const float* gn = p.gla_norm + l * 128;
; #pragma unroll
;         for (int g = 0; g < 4; ++g) {
;             const int dv = 32 * dvb + 8 * g + 4 * h2;
;             const u32x2 gw = *(const u32x2*)(grp + dv); const f32x4 gnv = *(const f32x4*)(gn + dv);
;             const float g0 = bflo(gw.x), g1 = bfhi(gw.x), g2 = bflo(gw.y), g3 = bfhi(gw.y);
;             const float v0 = acc[4 * g] * rstd * gnv[0] * (g0 * __builtin_amdgcn_rcpf(1.f + __expf(-g0))), v1 = acc[4 * g + 1] * rstd * gnv[1] * (g1 * __builtin_amdgcn_rcpf(1.f + __expf(-g1)));
;             const float v2 = acc[4 * g + 2] * rstd * gnv[2] * (g2 * __builtin_amdgcn_rcpf(1.f + __expf(-g2))), v3 = acc[4 * g + 3] * rstd * gnv[3] * (g3 * __builtin_amdgcn_rcpf(1.f + __expf(-g3)));
;             u32x2 wv; wv.x = cvt_pk_bf16(v0, v1); wv.y = cvt_pk_bf16(v2, v3); *(u32x2*)(op + dv) = wv;
;         }
;         __syncthreads();
	ds_read_b128 v[16:19], v16 offset:37120
	s_ashr_i32 s77, s76, 31
	v_mov_b64_e32 v[22:23], s[34:35]
	s_lshl_b64 s[0:1], s[76:77], 1
	s_add_i32 s2, s2, s70
	s_waitcnt lgkmcnt(0)
	v_mov_b32_e32 v20, v17
	v_mov_b32_e32 v21, v18
	v_mov_b32_e32 v17, v19
	v_add_f32_e32 v16, v20, v16
	v_add_f32_e32 v17, v21, v17
	v_lshl_or_b32 v21, v89, 2, s45
	v_add_f32_e32 v16, v16, v17
	v_fmamk_f32 v16, v16, 0x3c000000, v240
	v_cmp_gt_f32_e32 vcc, s85, v16
	v_mul_f32_e32 v17, 0x4b800000, v16
	v_lshlrev_b32_e32 v200, 1, v21
	v_cndmask_b32_e32 v16, v16, v17, vcc
	v_rsq_f32_e32 v16, v16
	s_movk_i32 s45, 0x1000
	v_lshlrev_b32_e32 v21, 2, v21
	s_add_u32 s92, s92, s74
	v_mul_f32_e32 v17, 0x45800000, v16
	v_cndmask_b32_e32 v20, v16, v17, vcc
	v_add_u32_e32 v16, s44, v90
	v_ashrrev_i32_e32 v17, 31, v16
	v_lshlrev_b64 v[18:19], 12, v[16:17]
	v_mad_i64_i32 v[16:17], s[4:5], v16, s56, v[22:23]
	v_lshl_add_u64 v[18:19], s[86:87], 0, v[18:19]
	v_lshl_add_u64 v[16:17], v[16:17], 0, s[0:1]
	v_lshl_add_u64 v[18:19], v[18:19], 0, s[0:1]
	v_lshl_add_u64 v[22:23], v[16:17], 0, v[200:201]
	s_mov_b64 s[0:1], 0x1600
	v_lshl_add_u64 v[16:17], v[22:23], 0, s[0:1]
	v_add_co_u32_e32 v22, vcc, s45, v22
	v_mul_f32_e32 v29, v0, v20
	s_nop 0
	v_addc_co_u32_e32 v23, vcc, 0, v23, vcc
	flat_load_dwordx2 v[26:27], v[22:23] offset:1536
	v_mul_f32_e32 v31, v2, v20
	global_load_dwordx4 v[22:25], v21, s[80:81]
	v_mul_f32_e32 v33, v3, v20
	v_lshl_add_u64 v[18:19], v[18:19], 0, v[200:201]
	s_mov_b64 s[0:1], 0x24300c00
	s_addc_u32 s93, s93, s75
	s_add_i32 s3, s3, s39
	s_cmpk_gt_i32 s2, 0x1ff
	s_waitcnt vmcnt(0) lgkmcnt(0)
	v_lshlrev_b32_e32 v28, 16, v26
	v_mul_f32_e32 v0, 0xbfb8aa3b, v28
	v_exp_f32_e32 v0, v0
	v_and_b32_e32 v26, 0xffff0000, v26
	v_mov_b32_e32 v35, v22
	v_lshlrev_b32_e32 v30, 16, v27
	v_add_f32_e32 v0, 1.0, v0
	v_rcp_f32_e32 v34, v0
	v_mul_f32_e32 v0, 0xbfb8aa3b, v26
	v_exp_f32_e32 v0, v0
	v_and_b32_e32 v32, 0xffff0000, v27
	v_mul_f32_e32 v27, v1, v20
	v_mul_f32_e32 v28, v34, v28
	v_mul_f32_e32 v29, v35, v29
	v_add_f32_e32 v0, 1.0, v0
	v_rcp_f32_e32 v22, v0
	v_mul_f32_e32 v28, v28, v29
	v_mul_f32_e32 v0, v22, v26
	v_mul_f32_e32 v1, v23, v27
	s_nop 0
	v_mul_f32_e32 v22, v0, v1
	v_mul_f32_e32 v0, 0xbfb8aa3b, v30
	v_exp_f32_e32 v0, v0
	v_mov_b32_e32 v1, v24
	v_cvt_pk_bf16_f32 v2, v28, v22
	v_mul_f32_e32 v26, v5, v20
	v_add_f32_e32 v0, 1.0, v0
	v_rcp_f32_e32 v0, v0
	v_mul_f32_e32 v28, v6, v20
	v_mul_f32_e32 v0, v0, v30
	v_mul_f32_e32 v1, v1, v31
	s_nop 0
	v_mul_f32_e32 v23, v0, v1
	v_mul_f32_e32 v0, 0xbfb8aa3b, v32
	v_exp_f32_e32 v0, v0
	s_nop 0
	v_add_f32_e32 v0, 1.0, v0
	v_rcp_f32_e32 v24, v0
	s_nop 0
	v_mul_f32_e32 v0, v24, v32
	v_mul_f32_e32 v1, v25, v33
	s_nop 0
	v_mul_f32_e32 v0, v0, v1
	v_cvt_pk_bf16_f32 v3, v23, v0
	v_lshl_add_u64 v[0:1], v[18:19], 0, s[0:1]
	s_mov_b32 s0, 0x24300000
	v_add_co_u32_e32 v18, vcc, s0, v18
	s_nop 1
	v_addc_co_u32_e32 v19, vcc, 0, v19, vcc
	flat_store_dwordx2 v[18:19], v[2:3] offset:3072
	flat_load_dwordx2 v[2:3], v[16:17] offset:16
	s_nop 0
	global_load_dwordx4 v[22:25], v21, s[80:81] offset:32
	v_mul_f32_e32 v18, v4, v20
	s_waitcnt vmcnt(0) lgkmcnt(0)
	v_lshlrev_b32_e32 v19, 16, v2
	v_and_b32_e32 v27, 0xffff0000, v2
	v_mul_f32_e32 v2, 0xbfb8aa3b, v19
	v_exp_f32_e32 v2, v2
	v_lshlrev_b32_e32 v29, 16, v3
	v_mov_b32_e32 v30, v22
	v_mov_b32_e32 v4, v23
	v_add_f32_e32 v2, 1.0, v2
	v_rcp_f32_e32 v31, v2
	v_mul_f32_e32 v2, 0xbfb8aa3b, v27
	v_exp_f32_e32 v2, v2
	v_and_b32_e32 v3, 0xffff0000, v3
	v_mul_f32_e32 v18, v30, v18
	v_mul_f32_e32 v19, v31, v19
	v_add_f32_e32 v2, 1.0, v2
	v_rcp_f32_e32 v5, v2
	v_mul_f32_e32 v2, 0xbfb8aa3b, v29
	v_exp_f32_e32 v2, v2
	v_mul_f32_e32 v18, v18, v19
	v_mul_f32_e32 v4, v4, v26
	v_mul_f32_e32 v5, v5, v27
	v_mul_f32_e32 v26, v8, v20
	v_add_f32_e32 v2, 1.0, v2
	v_mul_f32_e32 v19, v4, v5
	v_rcp_f32_e32 v5, v2
	v_mov_b32_e32 v4, v24
	v_mul_f32_e32 v2, v7, v20
	v_mul_f32_e32 v8, v9, v20
	v_mul_f32_e32 v4, v4, v28
	v_mul_f32_e32 v5, v5, v29
	s_nop 0
	v_mul_f32_e32 v6, v4, v5
	v_mul_f32_e32 v4, 0xbfb8aa3b, v3
	v_exp_f32_e32 v4, v4
	s_nop 0
	v_add_f32_e32 v4, 1.0, v4
	v_rcp_f32_e32 v5, v4
	v_mov_b32_e32 v4, v25
	v_mul_f32_e32 v2, v4, v2
	v_mul_f32_e32 v3, v5, v3
	s_nop 0
	v_mul_f32_e32 v3, v2, v3
	v_cvt_pk_bf16_f32 v2, v18, v19
	v_cvt_pk_bf16_f32 v3, v6, v3
	flat_store_dwordx2 v[0:1], v[2:3] offset:16
	flat_load_dwordx2 v[6:7], v[16:17] offset:32
	s_nop 0
	global_load_dwordx4 v[2:5], v21, s[80:81] offset:64
	s_waitcnt vmcnt(0) lgkmcnt(0)
	v_and_b32_e32 v23, 0xffff0000, v6
	v_mov_b32_e32 v18, v2
	v_mul_f32_e32 v2, 0xbfb8aa3b, v23
	v_exp_f32_e32 v2, v2
	v_mov_b32_e32 v22, v3
	v_lshlrev_b32_e32 v25, 16, v7
	v_mov_b32_e32 v24, v4
	v_add_f32_e32 v2, 1.0, v2
	v_rcp_f32_e32 v9, v2
	v_and_b32_e32 v7, 0xffff0000, v7
	v_lshlrev_b32_e32 v19, 16, v6
	v_mul_f32_e32 v6, 0xbfb8aa3b, v19
	v_mul_f32_e32 v2, v8, v22
	v_mul_f32_e32 v3, v9, v23
	v_exp_f32_e32 v6, v6
	v_mul_f32_e32 v8, v2, v3
	v_mul_f32_e32 v3, 0xbfb8aa3b, v25
	v_exp_f32_e32 v3, v3
	v_mul_f32_e32 v2, v10, v20
	v_add_f32_e32 v6, 1.0, v6
	v_rcp_f32_e32 v27, v6
	v_add_f32_e32 v3, 1.0, v3
	v_rcp_f32_e32 v3, v3
	v_mov_b32_e32 v6, v5
	v_mul_f32_e32 v18, v26, v18
	v_mul_f32_e32 v19, v27, v19
	v_mul_f32_e32 v2, v2, v24
	v_mul_f32_e32 v3, v3, v25
	s_nop 0
	v_mul_f32_e32 v4, v2, v3
	v_mul_f32_e32 v3, 0xbfb8aa3b, v7
	v_exp_f32_e32 v3, v3
	v_mul_f32_e32 v2, v11, v20
	v_mul_f32_e32 v18, v18, v19
	v_add_f32_e32 v3, 1.0, v3
	v_rcp_f32_e32 v3, v3
	s_nop 0
	v_mul_f32_e32 v2, v2, v6
	v_mul_f32_e32 v3, v3, v7
	s_nop 0
	v_mul_f32_e32 v3, v2, v3
	v_cvt_pk_bf16_f32 v2, v18, v8
	v_cvt_pk_bf16_f32 v3, v4, v3
	flat_store_dwordx2 v[0:1], v[2:3] offset:32
	flat_load_dwordx2 v[2:3], v[16:17] offset:48
	s_nop 0
	global_load_dwordx4 v[4:7], v21, s[80:81] offset:96
	v_mul_f32_e32 v18, v12, v20
	s_waitcnt vmcnt(0) lgkmcnt(0)
	v_lshlrev_b32_e32 v9, 16, v2
	v_and_b32_e32 v11, 0xffff0000, v2
	v_mul_f32_e32 v2, 0xbfb8aa3b, v9
	v_exp_f32_e32 v2, v2
	v_mov_b32_e32 v8, v4
	v_lshlrev_b32_e32 v17, 16, v3
	v_mov_b32_e32 v10, v5
	v_add_f32_e32 v2, 1.0, v2
	v_rcp_f32_e32 v19, v2
	v_mul_f32_e32 v2, 0xbfb8aa3b, v11
	v_exp_f32_e32 v2, v2
	v_and_b32_e32 v3, 0xffff0000, v3
	v_mul_f32_e32 v8, v18, v8
	v_mul_f32_e32 v9, v19, v9
	v_mov_b32_e32 v16, v6
	v_add_f32_e32 v2, 1.0, v2
	v_mul_f32_e32 v12, v8, v9
	v_rcp_f32_e32 v9, v2
	v_mul_f32_e32 v2, 0xbfb8aa3b, v17
	v_exp_f32_e32 v2, v2
	v_mul_f32_e32 v8, v13, v20
	v_mul_f32_e32 v4, v8, v10
	v_mul_f32_e32 v5, v9, v11
	v_add_f32_e32 v2, 1.0, v2
	v_mul_f32_e32 v8, v4, v5
	v_rcp_f32_e32 v5, v2
	v_mul_f32_e32 v2, 0xbfb8aa3b, v3
	v_exp_f32_e32 v2, v2
	v_mul_f32_e32 v4, v14, v20
	v_mul_f32_e32 v4, v4, v16
	v_mul_f32_e32 v5, v5, v17
	v_add_f32_e32 v2, 1.0, v2
	v_mul_f32_e32 v6, v4, v5
	v_rcp_f32_e32 v5, v2
	v_mul_f32_e32 v4, v15, v20
	v_mov_b32_e32 v2, v7
	v_mul_f32_e32 v2, v4, v2
	v_mul_f32_e32 v3, v5, v3
	s_nop 0
	v_mul_f32_e32 v3, v2, v3
	v_cvt_pk_bf16_f32 v2, v12, v8
	v_cvt_pk_bf16_f32 v3, v6, v3
	flat_store_dwordx2 v[0:1], v[2:3] offset:48
	s_waitcnt lgkmcnt(0)
	s_barrier
	s_cbranch_scc1 .LBB0_619

; #define LAS __attribute__((address_space(3)))
; __device__ __forceinline__ float bflo(unsigned w) { return __uint_as_float(w << 16); }
; __device__ __forceinline__ float bfhi(unsigned w) { return __uint_as_float(w & 0xffff0000u); }
; __device__ __forceinline__ float xsum(float v) { const auto r = __builtin_amdgcn_permlane32_swap(__float_as_uint(v), __float_as_uint(v), false, false); return __uint_as_float(r[0]) + __uint_as_float(r[1]); }
;     int tid = tid_in; asm volatile("" : "+v"(tid));
;     const int lane = tid & 63, r = lane & 31, hh = lane >> 5;
;     constexpr float SC = 0.08838834764831845f * LOG2E;
;     bf16x8 qf[8];
; #pragma unroll
;     for (int ks = 0; ks < 8; ++ks) qf[ks] = *(const bf16x8*)(Qrow + 16 * ks + 8 * hh);
;     f32x16 o[4];
; #pragma unroll
;     for (int db = 0; db < 4; ++db)
; #pragma unroll
;         for (int i = 0; i < 16; ++i) o[db][i] = 0.f;
;     float m = m_init, l = (hh == 0) ? l_init : 0.f;
;     const int pr = (r & ~12) | ((r & 4) << 1) | ((r & 8) >> 1);
;     const unsigned koff = pr * AT_KROW + 16 * hh, voff = AT_KBUF + r * AT_VROW + 16 * hh;
;     const int kkey0 = tid >> 4, kc16 = tid & 15, vd0 = tid >> 3, vc8 = tid & 7;
;     u32x4 kreg[2], vreg[2]; float creg = 0.f;
;     ...
;     float qn = 0.f; bool wdone = false;
;     LAS unsigned* flg = (LAS unsigned*)(lds + 2 * AT_BUF);
;     if (MODE == 0) {
; #pragma unroll
;         for (int ks = 0; ks < 8; ++ks) { const u32x4 qq = __builtin_bit_cast(u32x4, qf[ks]);
;             qn += bflo(qq.x) * bflo(qq.x) + bfhi(qq.x) * bfhi(qq.x) + bflo(qq.y) * bflo(qq.y) + bfhi(qq.y) * bfhi(qq.y) + bflo(qq.z) * bflo(qq.z) + bfhi(qq.z) * bfhi(qq.z) + bflo(qq.w) * bflo(qq.w) + bfhi(qq.w) * bfhi(qq.w); }
;         qn = xsum(qn); qn = sqrtf(qn) * kn * SC * 1.0001f + 1e-3f;
;     }
;     AT_LOAD(kt1 - 1); AT_WRITE(0); __syncthreads();
; __global__ void __launch_bounds__(512, 2) hybrid_fwd(Params p) {
;     ...
;                 asm volatile("s_waitcnt vmcnt(0)" ::: "memory"); __syncthreads();
;                 const int hd = c >> 5, qb = c & 31, tq0 = 256 * qb + 32 * wave, t_row = tq0 + (lane & 31);
;                 attn_unit<2>(lds, tid, QX + (size_t)t_row * 512 + hd * 128, KX + (size_t)l * 256 * 512 + hd * 128, 512, VXT + (size_t)l * 512 * 256 + (size_t)hd * 128 * 256, 256,
.LBB0_772:
	v_readlane_b32 s6, v255, 42
	v_readlane_b32 s7, v255, 43
	s_lshl_b64 s[10:11], s[6:7], 18
	s_and_b32 s12, s24, 31
	s_ashr_i32 s7, s25, 1
	s_lshl_b32 s6, s12, 8
	s_andn2_b32 s7, s7, 31
	s_add_i32 s7, s7, s6
	s_lshl_b32 s6, s4, 7
	v_and_or_b32 v0, v147, 31, s7
	s_ashr_i32 s7, s6, 31
	v_ashrrev_i32_e32 v1, 31, v0
	s_lshl_b64 s[8:9], s[6:7], 1
	v_lshlrev_b64 v[144:145], 9, v[0:1]
	v_lshlrev_b64 v[0:1], 10, v[0:1]
	s_add_u32 s13, s2, s10
	v_mov_b32_e32 v3, v147
	s_nop 0
	s_nop 0
	s_waitcnt vmcnt(0)
	s_waitcnt lgkmcnt(0)
	s_barrier
	v_lshl_add_u64 v[0:1], s[14:15], 0, v[0:1]
	s_addc_u32 s14, s3, s11
	v_lshl_add_u64 v[0:1], v[0:1], 0, s[8:9]
	v_bfe_u32 v2, v3, 5, 1
	s_add_u32 s10, s13, s8
	v_lshlrev_b32_e32 v200, 4, v2
	s_addc_u32 s11, s14, s9
	s_lshl_b64 s[4:5], s[4:5], 16
	v_lshlrev_b32_e32 v146, 3, v2
	v_lshl_add_u64 v[0:1], v[0:1], 0, v[200:201]
	v_lshlrev_b32_e32 v2, 1, v3
	v_lshrrev_b32_e32 v4, 1, v3
	s_add_u32 s4, s13, s4
	flat_load_dwordx4 v[96:99], v[0:1]
	flat_load_dwordx4 v[100:103], v[0:1] offset:32
	flat_load_dwordx4 v[104:107], v[0:1] offset:64
	flat_load_dwordx4 v[108:111], v[0:1] offset:96
	flat_load_dwordx4 v[112:115], v[0:1] offset:128
	flat_load_dwordx4 v[116:119], v[0:1] offset:160
	flat_load_dwordx4 v[120:123], v[0:1] offset:192
	flat_load_dwordx4 v[124:127], v[0:1] offset:224
	v_and_b32_e32 v0, 31, v3
	v_and_b32_e32 v1, 19, v3
	v_and_b32_e32 v2, 8, v2
	v_and_b32_e32 v4, 4, v4
	s_addc_u32 s5, s14, s5
	v_or3_b32 v1, v1, v2, v4
	s_movk_i32 s14, 0x110
	v_mul_u32_u24_e32 v159, 0x90, v0
	v_ashrrev_i32_e32 v0, 4, v3
	v_mad_u32_u24 v158, v1, s14, v200
	v_ashrrev_i32_e32 v1, 31, v0
	v_lshlrev_b64 v[4:5], 10, v[0:1]
	v_lshlrev_b32_e32 v1, 4, v3
	v_lshl_add_u64 v[6:7], s[10:11], 0, v[4:5]
	v_and_b32_e32 v148, 0xf0, v1
	v_mov_b32_e32 v149, v201
	v_lshl_add_u64 v[6:7], v[6:7], 0, v[148:149]
	s_mov_b32 s10, 0x27330000
	v_add_co_u32_e32 v8, vcc, s10, v6
	s_mov_b32 s10, 0x27338000
	s_nop 0
	v_addc_co_u32_e32 v9, vcc, 0, v7, vcc
	v_ashrrev_i32_e32 v2, 3, v3
	v_add_co_u32_e32 v6, vcc, s10, v6
	v_ashrrev_i32_e32 v3, 31, v2
	s_nop 0
	v_addc_co_u32_e32 v7, vcc, 0, v7, vcc
	flat_load_dwordx4 v[128:131], v[8:9]
	flat_load_dwordx4 v[132:135], v[6:7]
	v_lshlrev_b64 v[6:7], 9, v[2:3]
	v_lshl_add_u64 v[6:7], s[4:5], 0, v[6:7]
	v_and_b32_e32 v150, 0x70, v1
	v_mov_b32_e32 v151, v201
	v_lshl_add_u64 v[6:7], v[6:7], 0, v[150:151]
	s_mov_b64 s[4:5], 0x27400000
	v_lshl_add_u64 v[152:153], v[6:7], 0, s[4:5]
	s_mov_b64 s[4:5], 0x27408000
	v_lshl_add_u64 v[154:155], v[6:7], 0, s[4:5]
	flat_load_dwordx4 v[136:139], v[152:153] offset:384
	flat_load_dwordx4 v[140:143], v[154:155] offset:384
	v_mul_lo_u32 v151, v0, s14
	v_add3_u32 v0, 0, v151, v148
	v_mul_lo_u32 v160, v2, s83
	v_readlane_b32 s4, v255, 32
	v_readlane_b32 s5, v255, 33
	s_mov_b32 s13, 3
	v_add_u32_e32 v161, 0x2400, v160
	v_mov_b32_e32 v163, 0xf149f2ca
	s_movk_i32 s72, 0x80
	v_mov_b32_e32 v48, 0
	v_mov_b32_e32 v32, 0
	v_mov_b32_e32 v16, 0
	v_readlane_b32 s22, v255, 1
	s_waitcnt vmcnt(0) lgkmcnt(0)
	ds_write_b128 v0, v[128:131]
	ds_write_b128 v0, v[132:135] offset:8704
	v_add3_u32 v0, 0, v160, v150
	ds_write_b128 v0, v[136:139] offset:17408
	ds_write_b128 v0, v[140:143] offset:26624
	v_lshl_add_u64 v[0:1], s[4:5], 0, v[4:5]
	s_add_u32 s4, s2, s8
	v_lshl_add_u64 v[0:1], v[0:1], 0, v[148:149]
	s_addc_u32 s5, s3, s9
	v_mov_b32_e32 v149, 0
	v_lshl_add_u64 v[156:157], s[4:5], 0, v[0:1]
	v_mov_b32_e32 v49, v149
	v_mov_b32_e32 v50, v149
	v_mov_b32_e32 v51, v149
	v_mov_b32_e32 v52, v149
	v_mov_b32_e32 v53, v149
	v_mov_b32_e32 v54, v149
	v_mov_b32_e32 v55, v149
	v_mov_b32_e32 v56, v149
	v_mov_b32_e32 v57, v149
	v_mov_b32_e32 v58, v149
	v_mov_b32_e32 v59, v149
	v_mov_b32_e32 v60, v149
	v_mov_b32_e32 v61, v149
	v_mov_b32_e32 v62, v149
	v_mov_b32_e32 v63, v149
	v_mov_b32_e32 v33, v149
	v_mov_b32_e32 v34, v149
	v_mov_b32_e32 v35, v149
	v_mov_b32_e32 v36, v149
	v_mov_b32_e32 v37, v149
	v_mov_b32_e32 v38, v149
	v_mov_b32_e32 v39, v149
	v_mov_b32_e32 v40, v149
	v_mov_b32_e32 v41, v149
	v_mov_b32_e32 v42, v149
	v_mov_b32_e32 v43, v149
	v_mov_b32_e32 v44, v149
	v_mov_b32_e32 v45, v149
	v_mov_b32_e32 v46, v149
	v_mov_b32_e32 v47, v149
	v_mov_b32_e32 v17, v149
	v_mov_b32_e32 v18, v149
	v_mov_b32_e32 v19, v149
	v_mov_b32_e32 v20, v149
	v_mov_b32_e32 v21, v149
	v_mov_b32_e32 v22, v149
	v_mov_b32_e32 v23, v149
	v_mov_b32_e32 v24, v149
	v_mov_b32_e32 v25, v149
	v_mov_b32_e32 v26, v149
	v_mov_b32_e32 v27, v149
	v_mov_b32_e32 v28, v149
	v_mov_b32_e32 v29, v149
	v_mov_b32_e32 v30, v149
	v_mov_b32_e32 v31, v149
	v_mov_b32_e32 v0, 0
	v_mov_b32_e32 v1, v149
	v_mov_b32_e32 v2, v149
	v_mov_b32_e32 v3, v149
	v_mov_b32_e32 v4, v149
	v_mov_b32_e32 v5, v149
	v_mov_b32_e32 v6, v149
	v_mov_b32_e32 v7, v149
	v_mov_b32_e32 v8, v149
	v_mov_b32_e32 v9, v149
	v_mov_b32_e32 v10, v149
	v_mov_b32_e32 v11, v149
	v_mov_b32_e32 v12, v149
	v_mov_b32_e32 v13, v149
	v_mov_b32_e32 v14, v149
	v_mov_b32_e32 v15, v149
	s_waitcnt lgkmcnt(0)
	s_barrier
	s_cmpk_lg_i32 s72, 0xffc0
	s_cselect_b64 s[4:5], -1, 0
	s_cmpk_eq_i32 s72, 0xffc0
	s_cbranch_scc1 .LBB0_774
